# cache-policy A/B: P4 epilogue residual (x) loads with the default policy instead of nt
# baseline (speedup 1.0000x reference)
.LBB0_666:
	s_lshl_b32 s10, s6, 8
	s_add_i32 s1, s10, s38
	s_lshl_b32 s0, s7, 5
	v_or_b32_e32 v130, s1, v145
	s_lshl_b32 s1, s8, 8
	s_or_b32 s0, s1, s0
	v_lshrrev_b32_e32 v128, 2, v144
	v_ashrrev_i32_e32 v131, 31, v130
	v_and_or_b32 v128, v128, 12, s0
	v_lshlrev_b64 v[132:133], 13, v[130:131]
	v_ashrrev_i32_e32 v129, 31, v128
	v_lshl_add_u64 v[132:133], s[44:45], 0, v[132:133]
	v_lshl_add_u64 v[148:149], v[128:129], 2, v[132:133]
	s_barrier
	global_load_dwordx4 v[132:135], v[148:149], off
	global_load_dwordx4 v[136:139], v[148:149], off offset:64
	global_load_dwordx4 v[140:143], v[148:149], off offset:512
	global_load_dwordx4 v[150:153], v[148:149], off offset:576
	v_mbcnt_hi_u32_b32 v148, -1, v169
	v_and_b32_e32 v145, 64, v148
	v_and_b32_e32 v147, 63, v144
	v_xor_b32_e32 v144, 16, v148
	v_add_u32_e32 v154, 64, v145
	v_cmp_lt_i32_e32 vcc, v144, v154
	s_lshl_b32 s2, s7, 2
	s_add_i32 s4, s2, 0
	v_cndmask_b32_e32 v144, v148, v144, vcc
	v_lshlrev_b32_e32 v149, 2, v144
	v_cmp_gt_u32_e64 s[0:1], 16, v147
	s_waitcnt vmcnt(0)
	v_pk_add_f32 v[126:127], v[126:127], v[134:135]
	v_pk_add_f32 v[124:125], v[124:125], v[132:133]
	v_pk_add_f32 v[122:123], v[122:123], v[138:139]
	v_pk_add_f32 v[120:121], v[120:121], v[136:137]
	v_pk_add_f32 v[118:119], v[118:119], v[142:143]
	v_pk_add_f32 v[116:117], v[116:117], v[140:141]
	v_pk_mul_f32 v[132:133], v[126:127], v[126:127]
	v_pk_mul_f32 v[134:135], v[124:125], v[124:125]
	v_pk_mul_f32 v[136:137], v[122:123], v[122:123]
	v_pk_mul_f32 v[138:139], v[120:121], v[120:121]
	v_pk_add_f32 v[114:115], v[114:115], v[152:153]
	v_pk_add_f32 v[112:113], v[112:113], v[150:151]
	v_pk_mul_f32 v[140:141], v[118:119], v[118:119]
	v_pk_mul_f32 v[142:143], v[116:117], v[116:117]
	v_add_f32_e32 v136, v136, v137
	v_add_f32_e32 v137, v138, v139
	v_add_f32_e32 v132, v132, v133
	v_add_f32_e32 v133, v134, v135
	v_pk_mul_f32 v[144:145], v[114:115], v[114:115]
	v_pk_mul_f32 v[150:151], v[112:113], v[112:113]
	v_add_f32_e32 v134, v140, v141
	v_add_f32_e32 v135, v142, v143
	v_add_f32_e32 v136, v137, v136
	v_add_f32_e32 v132, v133, v132
	v_add_f32_e32 v138, v144, v145
	v_add_f32_e32 v139, v150, v151
	v_add_f32_e32 v133, v135, v134
	v_add_f32_e32 v132, v132, v136
	v_add_f32_e32 v132, v132, v133
	v_add_f32_e32 v133, v139, v138
	v_add_f32_e32 v132, v132, v133
	ds_bpermute_b32 v133, v149, v132
	v_xor_b32_e32 v134, 32, v148
	v_cmp_lt_i32_e32 vcc, v134, v154
	v_lshl_add_u32 v150, v146, 4, s4
	s_waitcnt lgkmcnt(0)
	v_add_f32_e32 v132, v132, v133
	v_cndmask_b32_e32 v134, v148, v134, vcc
	v_lshlrev_b32_e32 v151, 2, v134
	ds_bpermute_b32 v133, v151, v132
	s_and_saveexec_b64 s[2:3], s[0:1]
	s_cbranch_execz .LBB0_668
	s_waitcnt lgkmcnt(0)
	v_add_f32_e32 v132, v132, v133
	ds_write_b32 v150, v132
.LBB0_668:
	s_or_b64 exec, exec, s[2:3]
	v_or_b32_e32 v132, 16, v130
	s_waitcnt lgkmcnt(0)
	v_ashrrev_i32_e32 v133, 31, v132
	v_lshlrev_b64 v[132:133], 13, v[132:133]
	v_lshl_add_u64 v[132:133], s[44:45], 0, v[132:133]
	v_lshl_add_u64 v[144:145], v[128:129], 2, v[132:133]
	global_load_dwordx4 v[132:135], v[144:145], off
	global_load_dwordx4 v[136:139], v[144:145], off offset:64
	global_load_dwordx4 v[140:143], v[144:145], off offset:512
	global_load_dwordx4 v[152:155], v[144:145], off offset:576
	s_waitcnt vmcnt(3)
	v_pk_add_f32 v[110:111], v[110:111], v[134:135]
	v_pk_add_f32 v[108:109], v[108:109], v[132:133]
	s_waitcnt vmcnt(2)
	v_pk_add_f32 v[106:107], v[106:107], v[138:139]
	v_pk_add_f32 v[104:105], v[104:105], v[136:137]
	s_waitcnt vmcnt(1)
	v_pk_add_f32 v[102:103], v[102:103], v[142:143]
	v_pk_add_f32 v[100:101], v[100:101], v[140:141]
	v_pk_mul_f32 v[132:133], v[110:111], v[110:111]
	v_pk_mul_f32 v[134:135], v[108:109], v[108:109]
	v_pk_mul_f32 v[136:137], v[106:107], v[106:107]
	v_pk_mul_f32 v[138:139], v[104:105], v[104:105]
	s_waitcnt vmcnt(0)
	v_pk_add_f32 v[98:99], v[98:99], v[154:155]
	v_pk_add_f32 v[96:97], v[96:97], v[152:153]
	v_pk_mul_f32 v[140:141], v[102:103], v[102:103]
	v_pk_mul_f32 v[142:143], v[100:101], v[100:101]
	v_add_f32_e32 v136, v136, v137
	v_add_f32_e32 v137, v138, v139
	v_add_f32_e32 v132, v132, v133
	v_add_f32_e32 v133, v134, v135
	v_pk_mul_f32 v[144:145], v[98:99], v[98:99]
	v_pk_mul_f32 v[152:153], v[96:97], v[96:97]
	v_add_f32_e32 v134, v140, v141
	v_add_f32_e32 v135, v142, v143
	v_add_f32_e32 v136, v137, v136
	v_add_f32_e32 v132, v133, v132
	v_add_f32_e32 v138, v144, v145
	v_add_f32_e32 v139, v152, v153
	v_add_f32_e32 v133, v135, v134
	v_add_f32_e32 v132, v132, v136
	v_add_f32_e32 v132, v132, v133
	v_add_f32_e32 v133, v139, v138
	v_add_f32_e32 v132, v132, v133
	ds_bpermute_b32 v133, v149, v132
	s_waitcnt lgkmcnt(0)
	v_add_f32_e32 v132, v132, v133
	ds_bpermute_b32 v133, v151, v132
	s_and_saveexec_b64 s[2:3], s[0:1]
	s_cbranch_execz .LBB0_670
	s_waitcnt lgkmcnt(0)
	v_add_f32_e32 v132, v132, v133
	ds_write_b32 v150, v132 offset:256
.LBB0_670:
	s_or_b64 exec, exec, s[2:3]
	v_or_b32_e32 v132, 32, v130
	s_waitcnt lgkmcnt(0)
	v_ashrrev_i32_e32 v133, 31, v132
	v_lshlrev_b64 v[132:133], 13, v[132:133]
	v_lshl_add_u64 v[132:133], s[44:45], 0, v[132:133]
	v_lshl_add_u64 v[144:145], v[128:129], 2, v[132:133]
	global_load_dwordx4 v[132:135], v[144:145], off
	global_load_dwordx4 v[136:139], v[144:145], off offset:64
	global_load_dwordx4 v[140:143], v[144:145], off offset:512
	global_load_dwordx4 v[152:155], v[144:145], off offset:576
	s_waitcnt vmcnt(3)
	v_pk_add_f32 v[94:95], v[94:95], v[134:135]
	v_pk_add_f32 v[92:93], v[92:93], v[132:133]
	s_waitcnt vmcnt(2)
	v_pk_add_f32 v[90:91], v[90:91], v[138:139]
	v_pk_add_f32 v[88:89], v[88:89], v[136:137]
	s_waitcnt vmcnt(1)
	v_pk_add_f32 v[86:87], v[86:87], v[142:143]
	v_pk_add_f32 v[84:85], v[84:85], v[140:141]
	v_pk_mul_f32 v[132:133], v[94:95], v[94:95]
	v_pk_mul_f32 v[134:135], v[92:93], v[92:93]
	v_pk_mul_f32 v[136:137], v[90:91], v[90:91]
	v_pk_mul_f32 v[138:139], v[88:89], v[88:89]
	s_waitcnt vmcnt(0)
	v_pk_add_f32 v[82:83], v[82:83], v[154:155]
	v_pk_add_f32 v[80:81], v[80:81], v[152:153]
	v_pk_mul_f32 v[140:141], v[86:87], v[86:87]
	v_pk_mul_f32 v[142:143], v[84:85], v[84:85]
	v_add_f32_e32 v136, v136, v137
	v_add_f32_e32 v137, v138, v139
	v_add_f32_e32 v132, v132, v133
	v_add_f32_e32 v133, v134, v135
	v_pk_mul_f32 v[144:145], v[82:83], v[82:83]
	v_pk_mul_f32 v[152:153], v[80:81], v[80:81]
	v_add_f32_e32 v134, v140, v141
	v_add_f32_e32 v135, v142, v143
	v_add_f32_e32 v136, v137, v136
	v_add_f32_e32 v132, v133, v132
	v_add_f32_e32 v138, v144, v145
	v_add_f32_e32 v139, v152, v153
	v_add_f32_e32 v133, v135, v134
	v_add_f32_e32 v132, v132, v136
	v_add_f32_e32 v132, v132, v133
	v_add_f32_e32 v133, v139, v138
	v_add_f32_e32 v132, v132, v133
	ds_bpermute_b32 v133, v149, v132
	s_waitcnt lgkmcnt(0)
	v_add_f32_e32 v132, v132, v133
	ds_bpermute_b32 v133, v151, v132
	s_and_saveexec_b64 s[2:3], s[0:1]
	s_cbranch_execz .LBB0_672
	s_waitcnt lgkmcnt(0)
	v_add_f32_e32 v132, v132, v133
	ds_write_b32 v150, v132 offset:512
.LBB0_672:
	s_or_b64 exec, exec, s[2:3]
	v_or_b32_e32 v132, 48, v130
	s_waitcnt lgkmcnt(0)
	v_ashrrev_i32_e32 v133, 31, v132
	v_lshlrev_b64 v[132:133], 13, v[132:133]
	v_lshl_add_u64 v[132:133], s[44:45], 0, v[132:133]
	v_lshl_add_u64 v[144:145], v[128:129], 2, v[132:133]
	global_load_dwordx4 v[132:135], v[144:145], off
	global_load_dwordx4 v[136:139], v[144:145], off offset:64
	global_load_dwordx4 v[140:143], v[144:145], off offset:512
	global_load_dwordx4 v[152:155], v[144:145], off offset:576
	s_waitcnt vmcnt(3)
	v_pk_add_f32 v[78:79], v[78:79], v[134:135]
	v_pk_add_f32 v[76:77], v[76:77], v[132:133]
	s_waitcnt vmcnt(2)
	v_pk_add_f32 v[74:75], v[74:75], v[138:139]
	v_pk_add_f32 v[72:73], v[72:73], v[136:137]
	s_waitcnt vmcnt(1)
	v_pk_add_f32 v[70:71], v[70:71], v[142:143]
	v_pk_add_f32 v[68:69], v[68:69], v[140:141]
	v_pk_mul_f32 v[132:133], v[78:79], v[78:79]
	v_pk_mul_f32 v[134:135], v[76:77], v[76:77]
	v_pk_mul_f32 v[136:137], v[74:75], v[74:75]
	v_pk_mul_f32 v[138:139], v[72:73], v[72:73]
	s_waitcnt vmcnt(0)
	v_pk_add_f32 v[66:67], v[66:67], v[154:155]
	v_pk_add_f32 v[64:65], v[64:65], v[152:153]
	v_pk_mul_f32 v[140:141], v[70:71], v[70:71]
	v_pk_mul_f32 v[142:143], v[68:69], v[68:69]
	v_add_f32_e32 v136, v136, v137
	v_add_f32_e32 v137, v138, v139
	v_add_f32_e32 v132, v132, v133
	v_add_f32_e32 v133, v134, v135
	v_pk_mul_f32 v[144:145], v[66:67], v[66:67]
	v_pk_mul_f32 v[152:153], v[64:65], v[64:65]
	v_add_f32_e32 v134, v140, v141
	v_add_f32_e32 v135, v142, v143
	v_add_f32_e32 v136, v137, v136
	v_add_f32_e32 v132, v133, v132
	v_add_f32_e32 v138, v144, v145
	v_add_f32_e32 v139, v152, v153
	v_add_f32_e32 v133, v135, v134
	v_add_f32_e32 v132, v132, v136
	v_add_f32_e32 v132, v132, v133
	v_add_f32_e32 v133, v139, v138
	v_add_f32_e32 v132, v132, v133
	ds_bpermute_b32 v133, v149, v132
	s_waitcnt lgkmcnt(0)
	v_add_f32_e32 v132, v132, v133
	ds_bpermute_b32 v133, v151, v132
	s_and_saveexec_b64 s[2:3], s[0:1]
	s_cbranch_execz .LBB0_674
	s_waitcnt lgkmcnt(0)
	v_add_f32_e32 v132, v132, v133
	ds_write_b32 v150, v132 offset:768
.LBB0_674:
	s_or_b64 exec, exec, s[2:3]
	s_waitcnt lgkmcnt(0)
	v_lshlrev_b64 v[132:133], 13, v[130:131]
	v_lshl_add_u64 v[132:133], s[44:45], 0, v[132:133]
	v_lshl_add_u64 v[132:133], v[128:129], 2, v[132:133]
	s_mov_b64 s[2:3], 0x100000
	v_lshl_add_u64 v[152:153], v[132:133], 0, s[2:3]
	v_add_co_u32_e32 v142, vcc, 0x100000, v132
	global_load_dwordx4 v[134:137], v[152:153], off offset:64
	global_load_dwordx4 v[138:141], v[152:153], off offset:512
	v_addc_co_u32_e32 v143, vcc, 0, v133, vcc
	global_load_dwordx4 v[142:145], v[142:143], off
	s_nop 0
	global_load_dwordx4 v[152:155], v[152:153], off offset:576
	v_add_u32_e32 v148, 0x80, v146
	s_waitcnt vmcnt(3)
	v_pk_add_f32 v[58:59], v[58:59], v[136:137]
	v_pk_add_f32 v[56:57], v[56:57], v[134:135]
	s_waitcnt vmcnt(2)
	v_pk_add_f32 v[54:55], v[54:55], v[140:141]
	s_waitcnt vmcnt(1)
	v_pk_add_f32 v[62:63], v[62:63], v[144:145]
	v_pk_add_f32 v[60:61], v[60:61], v[142:143]
	v_pk_add_f32 v[52:53], v[52:53], v[138:139]
	v_pk_mul_f32 v[134:135], v[58:59], v[58:59]
	v_pk_mul_f32 v[136:137], v[56:57], v[56:57]
	v_pk_mul_f32 v[138:139], v[54:55], v[54:55]
	v_pk_mul_f32 v[142:143], v[62:63], v[62:63]
	v_pk_mul_f32 v[144:145], v[60:61], v[60:61]
	v_pk_mul_f32 v[140:141], v[52:53], v[52:53]
	s_waitcnt vmcnt(0)
	v_pk_add_f32 v[50:51], v[50:51], v[154:155]
	v_pk_add_f32 v[48:49], v[48:49], v[152:153]
	v_add_f32_e32 v134, v134, v135
	v_add_f32_e32 v135, v136, v137
	v_add_f32_e32 v136, v138, v139
	v_add_f32_e32 v138, v142, v143
	v_add_f32_e32 v139, v144, v145
	v_pk_mul_f32 v[152:153], v[50:51], v[50:51]
	v_pk_mul_f32 v[154:155], v[48:49], v[48:49]
	v_add_f32_e32 v137, v140, v141
	v_add_f32_e32 v134, v135, v134
	v_add_f32_e32 v138, v139, v138
	v_add_f32_e32 v135, v137, v136
	v_add_f32_e32 v136, v152, v153
	v_add_f32_e32 v137, v154, v155
	v_add_f32_e32 v134, v138, v134
	v_add_f32_e32 v134, v134, v135
	v_add_f32_e32 v135, v137, v136
	v_add_f32_e32 v134, v134, v135
	ds_bpermute_b32 v135, v149, v134
	s_waitcnt lgkmcnt(0)
	v_add_f32_e32 v134, v134, v135
	ds_bpermute_b32 v135, v151, v134
	s_and_saveexec_b64 s[2:3], s[0:1]
	s_cbranch_execz .LBB0_676
	v_lshl_add_u32 v136, v148, 4, s4
	s_waitcnt lgkmcnt(0)
	v_add_f32_e32 v134, v134, v135
	ds_write_b32 v136, v134
.LBB0_676:
	s_or_b64 exec, exec, s[2:3]
	v_add_co_u32_e32 v134, vcc, 0x120000, v132
	s_mov_b64 s[2:3], 0x120000
	s_waitcnt lgkmcnt(0)
	v_addc_co_u32_e32 v135, vcc, 0, v133, vcc
	global_load_dwordx4 v[134:137], v[134:135], off
	v_lshl_add_u64 v[132:133], v[132:133], 0, s[2:3]
	global_load_dwordx4 v[138:141], v[132:133], off offset:64
	global_load_dwordx4 v[142:145], v[132:133], off offset:512
	global_load_dwordx4 v[152:155], v[132:133], off offset:576
	s_waitcnt vmcnt(2)
	v_pk_add_f32 v[42:43], v[42:43], v[140:141]
	v_pk_add_f32 v[46:47], v[46:47], v[136:137]
	v_pk_add_f32 v[44:45], v[44:45], v[134:135]
	v_pk_add_f32 v[40:41], v[40:41], v[138:139]
	s_waitcnt vmcnt(1)
	v_pk_add_f32 v[38:39], v[38:39], v[144:145]
	v_pk_add_f32 v[36:37], v[36:37], v[142:143]
	v_pk_mul_f32 v[132:133], v[46:47], v[46:47]
	v_pk_mul_f32 v[134:135], v[44:45], v[44:45]
	v_pk_mul_f32 v[136:137], v[42:43], v[42:43]
	v_pk_mul_f32 v[138:139], v[40:41], v[40:41]
	s_waitcnt vmcnt(0)
	v_pk_add_f32 v[34:35], v[34:35], v[154:155]
	v_pk_add_f32 v[32:33], v[32:33], v[152:153]
	v_pk_mul_f32 v[140:141], v[38:39], v[38:39]
	v_pk_mul_f32 v[142:143], v[36:37], v[36:37]
	v_add_f32_e32 v132, v132, v133
	v_add_f32_e32 v133, v134, v135
	v_add_f32_e32 v134, v136, v137
	v_add_f32_e32 v135, v138, v139
	v_pk_mul_f32 v[144:145], v[34:35], v[34:35]
	v_pk_mul_f32 v[152:153], v[32:33], v[32:33]
	v_add_f32_e32 v136, v140, v141
	v_add_f32_e32 v137, v142, v143
	v_add_f32_e32 v132, v133, v132
	v_add_f32_e32 v133, v135, v134
	v_add_f32_e32 v138, v144, v145
	v_add_f32_e32 v139, v152, v153
	v_add_f32_e32 v134, v137, v136
	v_add_f32_e32 v132, v132, v133
	v_add_f32_e32 v132, v132, v134
	v_add_f32_e32 v133, v139, v138
	v_add_f32_e32 v132, v132, v133
	ds_bpermute_b32 v133, v149, v132
	s_waitcnt lgkmcnt(0)
	v_add_f32_e32 v132, v132, v133
	ds_bpermute_b32 v133, v151, v132
	s_and_saveexec_b64 s[2:3], s[0:1]
	s_cbranch_execz .LBB0_678
	s_waitcnt lgkmcnt(0)
	v_add_f32_e32 v132, v132, v133
	ds_write_b32 v150, v132 offset:2304
.LBB0_678:
	s_or_b64 exec, exec, s[2:3]
	v_lshlrev_b64 v[130:131], 13, v[130:131]
	v_lshl_add_u64 v[130:131], s[44:45], 0, v[130:131]
	v_lshl_add_u64 v[130:131], v[128:129], 2, v[130:131]
	s_mov_b64 s[2:3], 0x140000
	v_lshl_add_u64 v[144:145], v[130:131], 0, s[2:3]
	v_add_co_u32_e32 v140, vcc, 0x140000, v130
	s_waitcnt lgkmcnt(0)
	global_load_dwordx4 v[132:135], v[144:145], off offset:64
	global_load_dwordx4 v[136:139], v[144:145], off offset:512
	v_addc_co_u32_e32 v141, vcc, 0, v131, vcc
	global_load_dwordx4 v[140:143], v[140:141], off
	s_nop 0
	global_load_dwordx4 v[152:155], v[144:145], off offset:576
	s_waitcnt vmcnt(3)
	v_pk_add_f32 v[26:27], v[26:27], v[134:135]
	v_pk_add_f32 v[24:25], v[24:25], v[132:133]
	s_waitcnt vmcnt(2)
	v_pk_add_f32 v[22:23], v[22:23], v[138:139]
	s_waitcnt vmcnt(1)
	v_pk_add_f32 v[30:31], v[30:31], v[142:143]
	v_pk_add_f32 v[28:29], v[28:29], v[140:141]
	v_pk_add_f32 v[20:21], v[20:21], v[136:137]
	v_pk_mul_f32 v[132:133], v[26:27], v[26:27]
	v_pk_mul_f32 v[134:135], v[24:25], v[24:25]
	v_pk_mul_f32 v[136:137], v[22:23], v[22:23]
	v_pk_mul_f32 v[140:141], v[30:31], v[30:31]
	v_pk_mul_f32 v[142:143], v[28:29], v[28:29]
	v_pk_mul_f32 v[138:139], v[20:21], v[20:21]
	s_waitcnt vmcnt(0)
	v_pk_add_f32 v[18:19], v[18:19], v[154:155]
	v_pk_add_f32 v[16:17], v[16:17], v[152:153]
	v_add_f32_e32 v132, v132, v133
	v_add_f32_e32 v133, v134, v135
	v_add_f32_e32 v134, v136, v137
	v_add_f32_e32 v136, v140, v141
	v_add_f32_e32 v137, v142, v143
	v_pk_mul_f32 v[144:145], v[18:19], v[18:19]
	v_pk_mul_f32 v[152:153], v[16:17], v[16:17]
	v_add_f32_e32 v135, v138, v139
	v_add_f32_e32 v132, v133, v132
	v_add_f32_e32 v136, v137, v136
	v_add_f32_e32 v133, v135, v134
	v_add_f32_e32 v134, v144, v145
	v_add_f32_e32 v135, v152, v153
	v_add_f32_e32 v132, v136, v132
	v_add_f32_e32 v132, v132, v133
	v_add_f32_e32 v133, v135, v134
	v_add_f32_e32 v132, v132, v133
	ds_bpermute_b32 v133, v149, v132
	s_waitcnt lgkmcnt(0)
	v_add_f32_e32 v132, v132, v133
	ds_bpermute_b32 v133, v151, v132
	s_and_saveexec_b64 s[2:3], s[0:1]
	s_cbranch_execz .LBB0_680
	s_waitcnt lgkmcnt(0)
	v_add_f32_e32 v132, v132, v133
	ds_write_b32 v150, v132 offset:2560
.LBB0_680:
	s_or_b64 exec, exec, s[2:3]
	v_add_co_u32_e32 v132, vcc, 0x160000, v130
	s_mov_b64 s[2:3], 0x160000
	s_waitcnt lgkmcnt(0)
	v_addc_co_u32_e32 v133, vcc, 0, v131, vcc
	global_load_dwordx4 v[132:135], v[132:133], off
	v_lshl_add_u64 v[130:131], v[130:131], 0, s[2:3]
	global_load_dwordx4 v[136:139], v[130:131], off offset:64
	global_load_dwordx4 v[152:155], v[130:131], off offset:512
	global_load_dwordx4 v[156:159], v[130:131], off offset:576
	s_waitcnt vmcnt(2)
	v_pk_add_f32 v[138:139], v[10:11], v[138:139]
	v_pk_add_f32 v[142:143], v[14:15], v[134:135]
	v_pk_add_f32 v[144:145], v[12:13], v[132:133]
	v_pk_add_f32 v[140:141], v[8:9], v[136:137]
	s_waitcnt vmcnt(1)
	v_pk_add_f32 v[134:135], v[6:7], v[154:155]
	v_pk_add_f32 v[136:137], v[4:5], v[152:153]
	s_waitcnt vmcnt(0)
	v_pk_add_f32 v[130:131], v[2:3], v[158:159]
	v_pk_add_f32 v[132:133], v[0:1], v[156:157]
	v_pk_mul_f32 v[0:1], v[142:143], v[142:143]
	v_pk_mul_f32 v[2:3], v[144:145], v[144:145]
	v_pk_mul_f32 v[4:5], v[138:139], v[138:139]
	v_pk_mul_f32 v[6:7], v[140:141], v[140:141]
	v_pk_mul_f32 v[8:9], v[134:135], v[134:135]
	v_pk_mul_f32 v[10:11], v[136:137], v[136:137]
	v_add_f32_e32 v0, v0, v1
	v_add_f32_e32 v1, v2, v3
	v_add_f32_e32 v2, v4, v5
	v_add_f32_e32 v3, v6, v7
	v_pk_mul_f32 v[12:13], v[130:131], v[130:131]
	v_pk_mul_f32 v[14:15], v[132:133], v[132:133]
	v_add_f32_e32 v4, v8, v9
	v_add_f32_e32 v5, v10, v11
	v_add_f32_e32 v0, v1, v0
	v_add_f32_e32 v1, v3, v2
	v_add_f32_e32 v6, v12, v13
	v_add_f32_e32 v7, v14, v15
	v_add_f32_e32 v2, v5, v4
	v_add_f32_e32 v0, v0, v1
	v_add_f32_e32 v0, v0, v2
	v_add_f32_e32 v1, v7, v6
	v_add_f32_e32 v0, v0, v1
	ds_bpermute_b32 v1, v149, v0
	s_waitcnt lgkmcnt(0)
	v_add_f32_e32 v0, v0, v1
	ds_bpermute_b32 v1, v151, v0
	s_and_saveexec_b64 s[2:3], s[0:1]
	s_cbranch_execz .LBB0_682
	s_waitcnt lgkmcnt(0)
	v_add_f32_e32 v0, v0, v1
	ds_write_b32 v150, v0 offset:2816
